# v97 plus one 4-byte pad after the attention setup so later loop heads keep v86's 8-byte phases
# speedup vs baseline: 1.0113x; 1.0113x over previous
; #define LAS __attribute__((address_space(3)))
;     const int lane = tid & 63, r = lane & 31, hh = lane >> 5;
;     const int wave = __builtin_amdgcn_readfirstlane(tid >> 6), mi = wave & 1, g = wave >> 1;
;     const int w = bid, bh = w & 15, g16 = w >> 4, b = bh >> 3, h = bh & 7;
;     LAS float* lut = (LAS float*)(lds + AT_LUT); LAS float* ex = (LAS float*)lds;
;     const float NEG = -1e30f;
;     __syncthreads();
;     if (tid < 128) lut[tid] = lutg[h * 128 + tid] - rel_tab[31 * 8 + h] * LOG2E;
;     const bf16* kg = Kd + ((size_t)(b * SEQ)) * 1024 + h * 128 + (size_t)(tid >> 4) * 1024 + (tid & 15) * 8;
;     const bf16* vg = VTd + ((size_t)(bh * 128 + (tid >> 3))) * SEQ + (tid & 7) * 8;
;     const int kso = ((tid >> 4) * AT_KSTR + (tid & 15) * 8) * 2, vso = AT_VOFF + ((tid >> 3) * AT_VSTR + (tid & 7) * 8) * 2;
;     for (int ui = 0; ui < 4; ++ui) {
;         const int qb = ui == 0 ? g16 : (ui == 1 ? 31 - g16 : (ui == 2 ? 32 + g16 : 63 - g16));
;         const int qw = qb * 128 + 32 * g, NT = 2 * qb + 2, qabs = qw + r;
;         const bf16* qp = Qd + ((size_t)(b * SEQ + qabs)) * 1024 + h * 128 + 64 * mi + 8 * hh;
;         bf16x8_t qf[4];
; #pragma unroll
;         for (int ds = 0; ds < 4; ++ds) qf[ds] = *(const bf16x8_t*)(qp + 16 * ds);
;         f32x16 o[4];
; #pragma unroll
;         for (int dt = 0; dt < 4; ++dt)
; #pragma unroll
;             for (int i = 0; i < 16; ++i) o[dt][i] = 0.f;
;         float mref = 0.f, l = 0.f; bool first = true;
;         v4u kr0, kr1, vr0, vr1;
;         const int NTw = (qw + 31) / 64 + 1 < NT ? (qw + 31) / 64 + 1 : NT;
;         const bool isY = wave >= 4;
.LBB0_295:
	s_or_b64 exec, exec, s[28:29]
	s_lshl_b32 s24, s24, 7
	s_ashr_i32 s25, s24, 31
	s_lshl_b64 s[24:25], s[24:25], 2
	s_add_u32 s34, s40, s24
	s_addc_u32 s35, s41, s25
	s_ashr_i32 s26, s19, 6
	s_ashr_i32 s40, s19, 7
	s_lshl_b32 s19, s4, 10
	s_and_b32 s37, s19, 0x2000
	s_and_b32 s30, s26, 1
	s_and_b32 s24, s4, 15
	s_ashr_i32 s36, s4, 4
	s_lshl_b32 s19, s37, 11
	s_add_u32 s19, s6, s19
	v_ashrrev_i32_e32 v2, 4, v0
	s_addc_u32 s25, s7, 0
	s_lshl_b32 s27, s18, 1
	v_ashrrev_i32_e32 v3, 31, v2
	s_add_u32 s18, s19, s27
	v_lshlrev_b64 v[4:5], 11, v[2:3]
	v_lshlrev_b32_e32 v3, 3, v0
	s_addc_u32 s19, s25, 0
	v_and_b32_e32 v8, 0x78, v3
	v_lshl_add_u64 v[6:7], s[18:19], 0, v[4:5]
	v_lshlrev_b32_e32 v10, 1, v8
	v_mov_b32_e32 v11, v32
	v_ashrrev_i32_e32 v9, 3, v0
	v_lshl_add_u64 v[6:7], v[6:7], 0, v[10:11]
	v_lshl_add_u32 v10, s24, 7, v9
	v_ashrrev_i32_e32 v11, 31, v10
	v_lshlrev_b64 v[10:11], 14, v[10:11]
	v_and_b32_e32 v12, 56, v3
	s_mov_b64 s[18:19], 0x4300000
	v_lshl_add_u64 v[10:11], s[6:7], 0, v[10:11]
	v_lshlrev_b32_e32 v14, 1, v12
	v_mov_b32_e32 v15, v32
	v_lshl_add_u64 v[176:177], v[6:7], 0, s[18:19]
	v_lshl_add_u64 v[10:11], v[10:11], 0, v[14:15]
	s_mov_b64 s[18:19], 0x6300000
	s_movk_i32 s31, 0x88
	v_lshl_add_u64 v[178:179], v[10:11], 0, s[18:19]
	v_mad_u64_u32 v[2:3], s[18:19], v2, s31, v[8:9]
	s_movk_i32 s18, 0x48
	s_nop 0
	v_mad_u64_u32 v[8:9], s[18:19], v9, s18, v[12:13]
	s_lshl_b32 s42, s40, 5
	s_lshl_b32 s24, s30, 7
	s_add_u32 s18, s6, s27
	s_addc_u32 s19, s7, 0
	v_bfe_u32 v1, v0, 5, 1
	s_add_u32 s24, s18, s24
	s_addc_u32 s25, s19, 0
	v_lshlrev_b32_e32 v14, 4, v1
	v_lshl_add_u64 v[16:17], s[24:25], 0, v[14:15]
	s_mov_b64 s[24:25], 0x2300000
	s_cmp_gt_i32 s26, 3
	s_mov_b64 s[28:29], 0x4310000
	v_lshl_add_u64 v[180:181], v[16:17], 0, s[24:25]
	s_cselect_b64 s[24:25], -1, 0
	s_cmp_lt_i32 s26, 4
	v_lshl_add_u64 v[182:183], v[6:7], 0, s[28:29]
	s_mov_b64 s[28:29], 0x6400000
	s_cselect_b64 s[26:27], -1, 0
	v_lshl_add_u64 v[184:185], v[10:11], 0, s[28:29]
	s_mov_b64 s[28:29], 0x4320000
	s_sub_i32 s43, 31, s36
	s_add_i32 s44, s36, 32
	s_sub_i32 s45, 63, s36
	v_and_b32_e32 v218, 31, v0
	v_lshlrev_b32_e32 v12, 3, v1
	v_lshl_add_u64 v[186:187], v[6:7], 0, s[28:29]
	s_mov_b64 s[28:29], 0x4330000
	s_cmp_eq_u32 s30, 0
	v_lshl_add_u32 v219, v2, 1, 0
	v_lshl_add_u64 v[188:189], v[6:7], 0, s[28:29]
	v_mad_u32_u24 v2, v218, s31, v12
	s_cselect_b64 s[28:29], -1, 0
	s_cmp_eq_u32 s30, 1
	v_lshl_add_u32 v3, s30, 6, v2
	s_cselect_b64 s[30:31], -1, 0
	s_lshl_b32 s40, s40, 14
	v_mov_b32_e32 v13, v32
	v_lshl_add_u32 v221, v3, 1, 0
	v_add_u32_e32 v223, 0, v2
	v_lshl_add_u32 v223, v218, 3, v223
	v_lshl_add_u32 v223, v1, 3, v223
	s_add_i32 s40, s40, 0
	v_lshlrev_b32_e32 v2, 9, v1
	v_lshlrev_b32_e32 v3, 2, v218
	v_add3_u32 v224, s40, v2, v3
	v_lshl_add_u64 v[2:3], s[18:19], 0, v[12:13]
	s_mov_b64 s[18:19], 0xa300000
	v_lshl_add_u64 v[190:191], v[2:3], 0, s[18:19]
	v_not_b32_e32 v2, 16
	v_mad_i32_i24 v242, v1, -4, v2
	v_not_b32_e32 v2, 17
	v_mad_i32_i24 v243, v1, -4, v2
	v_not_b32_e32 v2, 18
	v_mad_i32_i24 v244, v1, -4, v2
	v_not_b32_e32 v2, 23
	v_mad_i32_i24 v245, v1, -4, v2
	v_not_b32_e32 v2, 24
	v_mad_i32_i24 v246, v1, -4, v2
	v_not_b32_e32 v2, 25
	s_lshl_b32 s4, s4, 21
	v_mad_i32_i24 v247, v1, -4, v2
	v_not_b32_e32 v2, 26
	s_and_b32 s94, s4, 0x1000000
	v_and_b32_e32 v0, 15, v0
	s_mov_b64 s[18:19], 0x4340000
	v_mad_i32_i24 v248, v1, -4, v2
	v_lshl_add_u64 v[2:3], s[94:95], 0, v[4:5]
	s_lshl_b32 s4, s5, 8
	v_lshlrev_b32_e32 v0, 4, v0
	v_lshl_add_u64 v[204:205], v[6:7], 0, s[18:19]
	s_mov_b64 s[18:19], 0x4350000
	v_or3_b32 v2, v2, s4, v0
	v_mul_i32_i24_e32 v222, -4, v1
	v_lshl_add_u64 v[206:207], v[6:7], 0, s[18:19]
	s_mov_b64 s[18:19], 0x6400080
	v_mad_i32_i24 v225, v1, -4, -1
	v_mad_i32_i24 v226, v1, -4, -2
	v_mad_i32_i24 v227, v1, -4, -3
	v_mad_i32_i24 v237, v1, -4, -8
	v_mad_i32_i24 v238, v1, -4, -9
	v_mad_i32_i24 v239, v1, -4, -10
	v_mad_i32_i24 v240, v1, -4, -11
	v_mad_i32_i24 v241, v1, -4, -16
	v_mad_i32_i24 v249, v1, -4, v218
	v_lshl_add_u64 v[0:1], s[6:7], 0, v[2:3]
	s_mov_b64 s[4:5], 0x4360000
	v_lshl_add_u32 v220, v8, 1, 0
	v_and_b32_e32 v230, 1, v228
	v_lshlrev_b32_e32 v230, 3, v230
	v_sub_u32_e32 v220, v220, v230
	s_nop 0
	s_mov_b32 s46, 0
	v_lshl_add_u64 v[192:193], s[34:35], 0, v[14:15]
	v_lshl_add_u64 v[208:209], v[10:11], 0, s[18:19]
	v_lshl_add_u64 v[210:211], v[0:1], 0, s[4:5]
	s_branch .LBB0_297
